# v8 = v7 + nt hint on P8 once-read loads
# baseline (speedup 1.0000x reference)
;     __device__ __forceinline__ void operator()(const f32x4 (&acc)[2][2][4][2], const Unit& u, int wr, int wc, int fr, int fq) const {
;     ...
; #pragma unroll
;         for (int ai = 0; ai < 2; ++ai)
; #pragma unroll
;             for (int m = 0; m < 4; ++m) {
;                 unsigned char* rowp = MIX + (size_t)(row0 + ai * HALF + m * 16) * DM + col0;
; #pragma unroll
;                 for (int bj = 0; bj < 2; ++bj) { const f32x4 v0 = acc[ai][bj][m][0] * *(const f32x4*)(pscale + col0 + bj * HALF), v1 = acc[ai][bj][m][1] * *(const f32x4*)(pscale + col0 + bj * HALF + 4); u32x2 w;
;                     w.x = pk4_fp8(v0[0], v0[1], v0[2], v0[3]); w.y = pk4_fp8(v1[0], v1[1], v1[2], v1[3]);
;                     *(u32x2*)(rowp + bj * HALF) = w; }
;             }
.LBB0_1009:
	v_lshl_or_b32 v144, s66, 8, v149
	v_readlane_b32 s68, v253, 6
	v_ashrrev_i32_e32 v145, 31, v144
	v_readlane_b32 s82, v253, 20
	v_readlane_b32 s83, v253, 21
	v_mov_b32_e32 v162, 0
	v_mov_b32_e32 v163, 0
	v_lshl_add_u64 v[142:143], v[144:145], 2, s[82:83]
	global_load_dwordx4 v[154:157], v[142:143], off nt
	global_load_dwordx4 v[158:161], v[142:143], off offset:16 nt
	v_lshl_add_u32 v146, s24, 8, v1
	v_ashrrev_i32_e32 v147, 31, v146
	s_mov_b32 s17, 0x40000
	s_mov_b64 s[26:27], 0x40000
	v_readlane_b32 s69, v253, 7
	v_readlane_b32 s70, v253, 8
	v_readlane_b32 s71, v253, 9
	v_readlane_b32 s72, v253, 10
	v_readlane_b32 s73, v253, 11
	v_readlane_b32 s74, v253, 12
	v_readlane_b32 s75, v253, 13
	v_readlane_b32 s76, v253, 14
	v_readlane_b32 s77, v253, 15
	v_readlane_b32 s78, v253, 16
	v_readlane_b32 s79, v253, 17
	v_readlane_b32 s80, v253, 18
	v_readlane_b32 s81, v253, 19
	s_waitcnt vmcnt(0)
	v_pk_mul_f32 v[122:123], v[122:123], v[154:155]
	v_pk_mul_f32 v[126:127], v[126:127], v[158:159]
	v_med3_f32 v122, v122, s64, v153
	v_med3_f32 v123, v123, s64, v153
	v_med3_f32 v126, v126, s64, v153
	v_med3_f32 v127, v127, s64, v153
	v_cvt_pk_fp8_f32 v162, v122, v123
	v_cvt_pk_fp8_f32 v163, v126, v127
	v_pk_mul_f32 v[124:125], v[124:125], v[156:157]
	v_pk_mul_f32 v[128:129], v[128:129], v[160:161]
	v_med3_f32 v124, v124, s64, v153
	v_med3_f32 v125, v125, s64, v153
	v_med3_f32 v122, v128, s64, v153
	v_med3_f32 v123, v129, s64, v153
	v_cvt_pk_fp8_f32 v162, v124, v125 op_sel:[0,0,1]
	v_cvt_pk_fp8_f32 v163, v122, v123 op_sel:[0,0,1]
	v_lshlrev_b64 v[122:123], 11, v[146:147]
	v_lshl_add_u64 v[122:123], s[4:5], 0, v[122:123]
	v_lshl_add_u64 v[122:123], v[122:123], 0, v[144:145]
	global_store_dwordx2 v[122:123], v[162:163], off
	global_load_dwordx4 v[124:127], v[142:143], off offset:512 nt
	global_load_dwordx4 v[154:157], v[142:143], off offset:528 nt
	v_mov_b32_e32 v128, 0
	v_mov_b32_e32 v129, 0
	s_waitcnt vmcnt(1)
	v_pk_mul_f32 v[114:115], v[114:115], v[124:125]
	s_waitcnt vmcnt(0)
	v_pk_mul_f32 v[118:119], v[118:119], v[154:155]
	v_med3_f32 v114, v114, s64, v153
	v_med3_f32 v115, v115, s64, v153
	v_med3_f32 v118, v118, s64, v153
	v_med3_f32 v119, v119, s64, v153
	v_cvt_pk_fp8_f32 v128, v114, v115
	v_cvt_pk_fp8_f32 v129, v118, v119
	v_pk_mul_f32 v[116:117], v[116:117], v[126:127]
	v_pk_mul_f32 v[120:121], v[120:121], v[156:157]
	v_med3_f32 v116, v116, s64, v153
	v_med3_f32 v117, v117, s64, v153
	v_med3_f32 v114, v120, s64, v153
	v_med3_f32 v115, v121, s64, v153
	v_cvt_pk_fp8_f32 v128, v116, v117 op_sel:[0,0,1]
	v_cvt_pk_fp8_f32 v129, v114, v115 op_sel:[0,0,1]
	v_mov_b32_e32 v124, 0
	v_mov_b32_e32 v125, 0
	v_or_b32_e32 v126, 16, v146
	global_store_dwordx2 v[122:123], v[128:129], off offset:128
	global_load_dwordx4 v[114:117], v[142:143], off nt
	global_load_dwordx4 v[118:121], v[142:143], off offset:16 nt
	v_ashrrev_i32_e32 v127, 31, v126
	s_waitcnt vmcnt(1)
	v_pk_mul_f32 v[106:107], v[106:107], v[114:115]
	s_waitcnt vmcnt(0)
	v_pk_mul_f32 v[110:111], v[110:111], v[118:119]
	v_med3_f32 v106, v106, s64, v153
	v_med3_f32 v107, v107, s64, v153
	v_med3_f32 v110, v110, s64, v153
	v_med3_f32 v111, v111, s64, v153
	v_cvt_pk_fp8_f32 v124, v106, v107
	v_cvt_pk_fp8_f32 v125, v110, v111
	v_pk_mul_f32 v[108:109], v[108:109], v[116:117]
	v_pk_mul_f32 v[112:113], v[112:113], v[120:121]
	v_med3_f32 v108, v108, s64, v153
	v_med3_f32 v109, v109, s64, v153
	v_med3_f32 v106, v112, s64, v153
	v_med3_f32 v107, v113, s64, v153
	v_cvt_pk_fp8_f32 v124, v108, v109 op_sel:[0,0,1]
	v_cvt_pk_fp8_f32 v125, v106, v107 op_sel:[0,0,1]
	v_lshlrev_b64 v[106:107], 11, v[126:127]
	v_lshl_add_u64 v[106:107], s[4:5], 0, v[106:107]
	v_lshl_add_u64 v[114:115], v[106:107], 0, v[144:145]
	global_store_dwordx2 v[114:115], v[124:125], off
	global_load_dwordx4 v[106:109], v[142:143], off offset:512 nt
	global_load_dwordx4 v[110:113], v[142:143], off offset:528 nt
	v_mov_b32_e32 v116, 0
	v_mov_b32_e32 v117, 0
	s_waitcnt vmcnt(1)
	v_pk_mul_f32 v[98:99], v[98:99], v[106:107]
	s_waitcnt vmcnt(0)
	v_pk_mul_f32 v[102:103], v[102:103], v[110:111]
	v_med3_f32 v98, v98, s64, v153
	v_med3_f32 v99, v99, s64, v153
	v_med3_f32 v102, v102, s64, v153
	v_med3_f32 v103, v103, s64, v153
	v_cvt_pk_fp8_f32 v116, v98, v99
	v_cvt_pk_fp8_f32 v117, v102, v103
	v_pk_mul_f32 v[100:101], v[100:101], v[108:109]
	v_pk_mul_f32 v[104:105], v[104:105], v[112:113]
	v_med3_f32 v100, v100, s64, v153
	v_med3_f32 v101, v101, s64, v153
	v_med3_f32 v98, v104, s64, v153
	v_med3_f32 v99, v105, s64, v153
	v_cvt_pk_fp8_f32 v116, v100, v101 op_sel:[0,0,1]
	v_cvt_pk_fp8_f32 v117, v98, v99 op_sel:[0,0,1]
	v_mov_b32_e32 v106, 0
	v_mov_b32_e32 v107, 0
	v_or_b32_e32 v108, 32, v146
	global_store_dwordx2 v[114:115], v[116:117], off offset:128
	global_load_dwordx4 v[98:101], v[142:143], off nt
	global_load_dwordx4 v[102:105], v[142:143], off offset:16 nt
	v_ashrrev_i32_e32 v109, 31, v108
	s_waitcnt vmcnt(1)
	v_pk_mul_f32 v[90:91], v[90:91], v[98:99]
	s_waitcnt vmcnt(0)
	v_pk_mul_f32 v[94:95], v[94:95], v[102:103]
	v_med3_f32 v90, v90, s64, v153
	v_med3_f32 v91, v91, s64, v153
	v_med3_f32 v94, v94, s64, v153
	v_med3_f32 v95, v95, s64, v153
	v_cvt_pk_fp8_f32 v106, v90, v91
	v_cvt_pk_fp8_f32 v107, v94, v95
	v_pk_mul_f32 v[92:93], v[92:93], v[100:101]
	v_pk_mul_f32 v[96:97], v[96:97], v[104:105]
	v_med3_f32 v92, v92, s64, v153
	v_med3_f32 v93, v93, s64, v153
	v_med3_f32 v90, v96, s64, v153
	v_med3_f32 v91, v97, s64, v153
	v_cvt_pk_fp8_f32 v106, v92, v93 op_sel:[0,0,1]
	v_cvt_pk_fp8_f32 v107, v90, v91 op_sel:[0,0,1]
	v_lshlrev_b64 v[90:91], 11, v[108:109]
	v_lshl_add_u64 v[90:91], s[4:5], 0, v[90:91]
	v_lshl_add_u64 v[98:99], v[90:91], 0, v[144:145]
	global_store_dwordx2 v[98:99], v[106:107], off
	global_load_dwordx4 v[90:93], v[142:143], off offset:512 nt
	global_load_dwordx4 v[94:97], v[142:143], off offset:528 nt
	v_mov_b32_e32 v100, 0
	v_mov_b32_e32 v101, 0
	s_waitcnt vmcnt(1)
;     __device__ __forceinline__ void operator()(const f32x4 (&acc)[2][2][4][2], const Unit& u, int wr, int wc, int fr, int fq) const {
;     ...
; #pragma unroll
;         for (int ai = 0; ai < 2; ++ai)
; #pragma unroll
;             for (int m = 0; m < 4; ++m) {
;                 unsigned char* rowp = MIX + (size_t)(row0 + ai * HALF + m * 16) * DM + col0;
; #pragma unroll
;                 for (int bj = 0; bj < 2; ++bj) { const f32x4 v0 = acc[ai][bj][m][0] * *(const f32x4*)(pscale + col0 + bj * HALF), v1 = acc[ai][bj][m][1] * *(const f32x4*)(pscale + col0 + bj * HALF + 4); u32x2 w;
;                     w.x = pk4_fp8(v0[0], v0[1], v0[2], v0[3]); w.y = pk4_fp8(v1[0], v1[1], v1[2], v1[3]);
;                     *(u32x2*)(rowp + bj * HALF) = w; }
;             }
	v_pk_mul_f32 v[82:83], v[82:83], v[90:91]
	s_waitcnt vmcnt(0)
	v_pk_mul_f32 v[86:87], v[86:87], v[94:95]
	v_med3_f32 v82, v82, s64, v153
	v_med3_f32 v83, v83, s64, v153
	v_med3_f32 v86, v86, s64, v153
	v_med3_f32 v87, v87, s64, v153
	v_cvt_pk_fp8_f32 v100, v82, v83
	v_cvt_pk_fp8_f32 v101, v86, v87
	v_pk_mul_f32 v[84:85], v[84:85], v[92:93]
	v_pk_mul_f32 v[88:89], v[88:89], v[96:97]
	v_med3_f32 v84, v84, s64, v153
	v_med3_f32 v85, v85, s64, v153
	v_med3_f32 v82, v88, s64, v153
	v_med3_f32 v83, v89, s64, v153
	v_cvt_pk_fp8_f32 v100, v84, v85 op_sel:[0,0,1]
	v_cvt_pk_fp8_f32 v101, v82, v83 op_sel:[0,0,1]
	v_mov_b32_e32 v90, 0
	v_mov_b32_e32 v91, 0
	v_or_b32_e32 v92, 48, v146
	global_store_dwordx2 v[98:99], v[100:101], off offset:128
	global_load_dwordx4 v[82:85], v[142:143], off nt
	global_load_dwordx4 v[86:89], v[142:143], off offset:16 nt
	v_ashrrev_i32_e32 v93, 31, v92
	s_waitcnt vmcnt(1)
	v_pk_mul_f32 v[74:75], v[74:75], v[82:83]
	s_waitcnt vmcnt(0)
	v_pk_mul_f32 v[78:79], v[78:79], v[86:87]
	v_med3_f32 v74, v74, s64, v153
	v_med3_f32 v75, v75, s64, v153
	v_med3_f32 v78, v78, s64, v153
	v_med3_f32 v79, v79, s64, v153
	v_cvt_pk_fp8_f32 v90, v74, v75
	v_cvt_pk_fp8_f32 v91, v78, v79
	v_pk_mul_f32 v[76:77], v[76:77], v[84:85]
	v_pk_mul_f32 v[80:81], v[80:81], v[88:89]
	v_med3_f32 v76, v76, s64, v153
	v_med3_f32 v77, v77, s64, v153
	v_med3_f32 v74, v80, s64, v153
	v_med3_f32 v75, v81, s64, v153
	v_cvt_pk_fp8_f32 v90, v76, v77 op_sel:[0,0,1]
	v_cvt_pk_fp8_f32 v91, v74, v75 op_sel:[0,0,1]
	v_lshlrev_b64 v[74:75], 11, v[92:93]
	v_lshl_add_u64 v[74:75], s[4:5], 0, v[74:75]
	v_lshl_add_u64 v[82:83], v[74:75], 0, v[144:145]
	global_store_dwordx2 v[82:83], v[90:91], off
	global_load_dwordx4 v[74:77], v[142:143], off offset:512 nt
	global_load_dwordx4 v[78:81], v[142:143], off offset:528 nt
	v_mov_b32_e32 v84, 0
	v_mov_b32_e32 v85, 0
	s_waitcnt vmcnt(1)
	v_pk_mul_f32 v[66:67], v[66:67], v[74:75]
	s_waitcnt vmcnt(0)
	v_pk_mul_f32 v[70:71], v[70:71], v[78:79]
	v_med3_f32 v66, v66, s64, v153
	v_med3_f32 v67, v67, s64, v153
	v_med3_f32 v70, v70, s64, v153
	v_med3_f32 v71, v71, s64, v153
	v_cvt_pk_fp8_f32 v84, v66, v67
	v_cvt_pk_fp8_f32 v85, v70, v71
	v_pk_mul_f32 v[68:69], v[68:69], v[76:77]
	v_pk_mul_f32 v[72:73], v[72:73], v[80:81]
	v_med3_f32 v68, v68, s64, v153
	v_med3_f32 v69, v69, s64, v153
	v_med3_f32 v66, v72, s64, v153
	v_med3_f32 v67, v73, s64, v153
	v_cvt_pk_fp8_f32 v84, v68, v69 op_sel:[0,0,1]
	v_cvt_pk_fp8_f32 v85, v66, v67 op_sel:[0,0,1]
	v_mov_b32_e32 v74, 0
	v_mov_b32_e32 v75, 0
	global_store_dwordx2 v[82:83], v[84:85], off offset:128
	global_load_dwordx4 v[66:69], v[142:143], off nt
	global_load_dwordx4 v[70:73], v[142:143], off offset:16 nt
	s_waitcnt vmcnt(1)
	v_pk_mul_f32 v[58:59], v[58:59], v[66:67]
	s_waitcnt vmcnt(0)
	v_pk_mul_f32 v[62:63], v[62:63], v[70:71]
	v_med3_f32 v58, v58, s64, v153
	v_med3_f32 v59, v59, s64, v153
	v_med3_f32 v62, v62, s64, v153
	v_med3_f32 v63, v63, s64, v153
	v_cvt_pk_fp8_f32 v74, v58, v59
	v_cvt_pk_fp8_f32 v75, v62, v63
	v_pk_mul_f32 v[60:61], v[60:61], v[68:69]
	v_pk_mul_f32 v[64:65], v[64:65], v[72:73]
	v_med3_f32 v60, v60, s64, v153
	v_med3_f32 v61, v61, s64, v153
	v_med3_f32 v58, v64, s64, v153
	v_med3_f32 v59, v65, s64, v153
	v_cvt_pk_fp8_f32 v74, v60, v61 op_sel:[0,0,1]
	v_cvt_pk_fp8_f32 v75, v58, v59 op_sel:[0,0,1]
	v_add_co_u32_e32 v58, vcc, s17, v122
	v_mov_b32_e32 v66, 0
	s_nop 0
	v_addc_co_u32_e32 v59, vcc, 0, v123, vcc
	global_store_dwordx2 v[58:59], v[74:75], off
	global_load_dwordx4 v[58:61], v[142:143], off offset:512 nt
	s_nop 0
	global_load_dwordx4 v[62:65], v[142:143], off offset:528 nt
	v_mov_b32_e32 v67, 0
	s_mov_b32 s17, 0x48000
	s_waitcnt vmcnt(1)
	v_pk_mul_f32 v[50:51], v[50:51], v[58:59]
	s_waitcnt vmcnt(0)
	v_pk_mul_f32 v[54:55], v[54:55], v[62:63]
	v_med3_f32 v50, v50, s64, v153
	v_med3_f32 v51, v51, s64, v153
	v_med3_f32 v54, v54, s64, v153
	v_med3_f32 v55, v55, s64, v153
	v_cvt_pk_fp8_f32 v66, v50, v51
	v_cvt_pk_fp8_f32 v67, v54, v55
	v_pk_mul_f32 v[52:53], v[52:53], v[60:61]
	v_pk_mul_f32 v[56:57], v[56:57], v[64:65]
	v_med3_f32 v52, v52, s64, v153
	v_med3_f32 v53, v53, s64, v153
	v_med3_f32 v50, v56, s64, v153
	v_med3_f32 v51, v57, s64, v153
	v_cvt_pk_fp8_f32 v66, v52, v53 op_sel:[0,0,1]
	v_cvt_pk_fp8_f32 v67, v50, v51 op_sel:[0,0,1]
	v_lshl_add_u64 v[50:51], v[122:123], 0, s[26:27]
	v_mov_b32_e32 v58, 0
	v_mov_b32_e32 v59, 0
	global_store_dwordx2 v[50:51], v[66:67], off offset:128
	global_load_dwordx4 v[50:53], v[142:143], off nt
	s_nop 0
	global_load_dwordx4 v[54:57], v[142:143], off offset:16 nt
	s_mov_b64 s[26:27], 0x48000
	s_waitcnt vmcnt(1)
	v_pk_mul_f32 v[42:43], v[42:43], v[50:51]
	s_waitcnt vmcnt(0)
;     __device__ __forceinline__ void operator()(const f32x4 (&acc)[2][2][4][2], const Unit& u, int wr, int wc, int fr, int fq) const {
;     ...
; #pragma unroll
;         for (int ai = 0; ai < 2; ++ai)
; #pragma unroll
;             for (int m = 0; m < 4; ++m) {
;                 unsigned char* rowp = MIX + (size_t)(row0 + ai * HALF + m * 16) * DM + col0;
; #pragma unroll
;                 for (int bj = 0; bj < 2; ++bj) { const f32x4 v0 = acc[ai][bj][m][0] * *(const f32x4*)(pscale + col0 + bj * HALF), v1 = acc[ai][bj][m][1] * *(const f32x4*)(pscale + col0 + bj * HALF + 4); u32x2 w;
;                     w.x = pk4_fp8(v0[0], v0[1], v0[2], v0[3]); w.y = pk4_fp8(v1[0], v1[1], v1[2], v1[3]);
;                     *(u32x2*)(rowp + bj * HALF) = w; }
;             }
	v_pk_mul_f32 v[46:47], v[46:47], v[54:55]
	v_med3_f32 v42, v42, s64, v153
	v_med3_f32 v43, v43, s64, v153
	v_med3_f32 v46, v46, s64, v153
	v_med3_f32 v47, v47, s64, v153
	v_cvt_pk_fp8_f32 v58, v42, v43
	v_cvt_pk_fp8_f32 v59, v46, v47
	v_pk_mul_f32 v[44:45], v[44:45], v[52:53]
	v_pk_mul_f32 v[48:49], v[48:49], v[56:57]
	v_med3_f32 v44, v44, s64, v153
	v_med3_f32 v45, v45, s64, v153
	v_med3_f32 v42, v48, s64, v153
	v_med3_f32 v43, v49, s64, v153
	v_cvt_pk_fp8_f32 v58, v44, v45 op_sel:[0,0,1]
	v_cvt_pk_fp8_f32 v59, v42, v43 op_sel:[0,0,1]
	v_add_co_u32_e32 v42, vcc, s17, v122
	v_mov_b32_e32 v50, 0
	s_nop 0
	v_addc_co_u32_e32 v43, vcc, 0, v123, vcc
	global_store_dwordx2 v[42:43], v[58:59], off
	global_load_dwordx4 v[42:45], v[142:143], off offset:512 nt
	s_nop 0
	global_load_dwordx4 v[46:49], v[142:143], off offset:528 nt
	v_mov_b32_e32 v51, 0
	s_mov_b32 s17, 0x50000
	s_waitcnt vmcnt(1)
	v_pk_mul_f32 v[34:35], v[34:35], v[42:43]
	s_waitcnt vmcnt(0)
	v_pk_mul_f32 v[38:39], v[38:39], v[46:47]
	v_med3_f32 v34, v34, s64, v153
	v_med3_f32 v35, v35, s64, v153
	v_med3_f32 v38, v38, s64, v153
	v_med3_f32 v39, v39, s64, v153
	v_cvt_pk_fp8_f32 v50, v34, v35
	v_cvt_pk_fp8_f32 v51, v38, v39
	v_pk_mul_f32 v[36:37], v[36:37], v[44:45]
	v_pk_mul_f32 v[40:41], v[40:41], v[48:49]
	v_med3_f32 v36, v36, s64, v153
	v_med3_f32 v37, v37, s64, v153
	v_med3_f32 v34, v40, s64, v153
	v_med3_f32 v35, v41, s64, v153
	v_cvt_pk_fp8_f32 v50, v36, v37 op_sel:[0,0,1]
	v_cvt_pk_fp8_f32 v51, v34, v35 op_sel:[0,0,1]
	v_lshl_add_u64 v[34:35], v[122:123], 0, s[26:27]
	v_mov_b32_e32 v42, 0
	v_mov_b32_e32 v43, 0
	global_store_dwordx2 v[34:35], v[50:51], off offset:128
	global_load_dwordx4 v[34:37], v[142:143], off nt
	s_nop 0
	global_load_dwordx4 v[38:41], v[142:143], off offset:16 nt
	s_mov_b64 s[26:27], 0x50000
	s_waitcnt vmcnt(1)
	v_pk_mul_f32 v[26:27], v[26:27], v[34:35]
	s_waitcnt vmcnt(0)
	v_pk_mul_f32 v[30:31], v[30:31], v[38:39]
	v_med3_f32 v26, v26, s64, v153
	v_med3_f32 v27, v27, s64, v153
	v_med3_f32 v30, v30, s64, v153
	v_med3_f32 v31, v31, s64, v153
	v_cvt_pk_fp8_f32 v42, v26, v27
	v_cvt_pk_fp8_f32 v43, v30, v31
	v_pk_mul_f32 v[28:29], v[28:29], v[36:37]
	v_pk_mul_f32 v[32:33], v[32:33], v[40:41]
	v_med3_f32 v28, v28, s64, v153
	v_med3_f32 v29, v29, s64, v153
	v_med3_f32 v26, v32, s64, v153
	v_med3_f32 v27, v33, s64, v153
	v_cvt_pk_fp8_f32 v42, v28, v29 op_sel:[0,0,1]
	v_cvt_pk_fp8_f32 v43, v26, v27 op_sel:[0,0,1]
	v_add_co_u32_e32 v26, vcc, s17, v122
	v_mov_b32_e32 v34, 0
	s_nop 0
	v_addc_co_u32_e32 v27, vcc, 0, v123, vcc
	global_store_dwordx2 v[26:27], v[42:43], off
	global_load_dwordx4 v[26:29], v[142:143], off offset:512 nt
	s_nop 0
	global_load_dwordx4 v[30:33], v[142:143], off offset:528 nt
	v_mov_b32_e32 v35, 0
	s_waitcnt vmcnt(1)
	v_pk_mul_f32 v[18:19], v[18:19], v[26:27]
	s_waitcnt vmcnt(0)
	v_pk_mul_f32 v[22:23], v[22:23], v[30:31]
	v_med3_f32 v18, v18, s64, v153
	v_med3_f32 v19, v19, s64, v153
	v_med3_f32 v22, v22, s64, v153
	v_med3_f32 v23, v23, s64, v153
	v_cvt_pk_fp8_f32 v34, v18, v19
	v_cvt_pk_fp8_f32 v35, v22, v23
	v_pk_mul_f32 v[20:21], v[20:21], v[28:29]
	v_pk_mul_f32 v[24:25], v[24:25], v[32:33]
	v_med3_f32 v20, v20, s64, v153
	v_med3_f32 v21, v21, s64, v153
	v_med3_f32 v18, v24, s64, v153
	v_med3_f32 v19, v25, s64, v153
	v_cvt_pk_fp8_f32 v34, v20, v21 op_sel:[0,0,1]
	v_cvt_pk_fp8_f32 v35, v18, v19 op_sel:[0,0,1]
	v_lshl_add_u64 v[18:19], v[122:123], 0, s[26:27]
	v_mov_b32_e32 v26, 0
	v_mov_b32_e32 v27, 0
	global_store_dwordx2 v[18:19], v[34:35], off offset:128
	global_load_dwordx4 v[18:21], v[142:143], off nt
	s_nop 0
	global_load_dwordx4 v[22:25], v[142:143], off offset:16 nt
	s_mov_b64 s[26:27], 0x58000
	s_waitcnt vmcnt(1)
	v_pk_mul_f32 v[10:11], v[10:11], v[18:19]
	s_waitcnt vmcnt(0)
	v_pk_mul_f32 v[14:15], v[14:15], v[22:23]
	v_med3_f32 v10, v10, s64, v153
	v_med3_f32 v11, v11, s64, v153
	v_med3_f32 v14, v14, s64, v153
	v_med3_f32 v15, v15, s64, v153
	v_cvt_pk_fp8_f32 v26, v10, v11
	v_cvt_pk_fp8_f32 v27, v14, v15
	v_pk_mul_f32 v[12:13], v[12:13], v[20:21]
	v_pk_mul_f32 v[16:17], v[16:17], v[24:25]
	v_med3_f32 v12, v12, s64, v153
	v_med3_f32 v13, v13, s64, v153
	v_med3_f32 v10, v16, s64, v153
	v_med3_f32 v11, v17, s64, v153
	v_cvt_pk_fp8_f32 v26, v12, v13 op_sel:[0,0,1]
	v_cvt_pk_fp8_f32 v27, v10, v11 op_sel:[0,0,1]
	v_add_co_u32_e32 v10, vcc, s65, v122
	v_mov_b32_e32 v18, 0
	s_nop 0
	v_addc_co_u32_e32 v11, vcc, 0, v123, vcc
	global_store_dwordx2 v[10:11], v[26:27], off
	global_load_dwordx4 v[10:13], v[142:143], off offset:512 nt
	s_nop 0
	global_load_dwordx4 v[14:17], v[142:143], off offset:528 nt
	v_mov_b32_e32 v19, 0
	s_andn2_b64 vcc, exec, s[2:3]
	s_mov_b64 s[2:3], -1
	s_waitcnt vmcnt(1)
	v_pk_mul_f32 v[2:3], v[2:3], v[10:11]
	s_waitcnt vmcnt(0)
	v_pk_mul_f32 v[6:7], v[6:7], v[14:15]
	v_med3_f32 v2, v2, s64, v153
	v_med3_f32 v3, v3, s64, v153
	v_med3_f32 v6, v6, s64, v153
	v_med3_f32 v7, v7, s64, v153
	v_cvt_pk_fp8_f32 v18, v2, v3
	v_cvt_pk_fp8_f32 v19, v6, v7
	v_pk_mul_f32 v[4:5], v[4:5], v[12:13]
	v_pk_mul_f32 v[8:9], v[8:9], v[16:17]
	v_med3_f32 v4, v4, s64, v153
	v_med3_f32 v5, v5, s64, v153
	v_med3_f32 v2, v8, s64, v153
	v_med3_f32 v3, v9, s64, v153
	v_cvt_pk_fp8_f32 v18, v4, v5 op_sel:[0,0,1]
	v_cvt_pk_fp8_f32 v19, v2, v3 op_sel:[0,0,1]
	v_lshl_add_u64 v[2:3], v[122:123], 0, s[26:27]
	global_store_dwordx2 v[2:3], v[18:19], off offset:128
	s_cbranch_vccnz .LBB0_1004
	s_andn2_b64 vcc, exec, s[0:1]
	s_cbranch_vccnz .LBB0_1003
	s_barrier
	s_branch .LBB0_1003

; #define GAS __attribute__((address_space(1)))
; __device__ __forceinline__ float silu1(float x) { return x * __builtin_amdgcn_rcpf(1.0f + __builtin_amdgcn_exp2f(-1.4426950408889634f * x)); }
; __device__ __forceinline__ void retS_unit(Frame& F, const Args& A, int unit) {
;     ...
;         const float ss = wave_sum((o[0] * o[0] + o[1] * o[1]) + (o[2] * o[2] + o[3] * o[3]));
;         const float rs = 1.0f / sqrtf(ss * (1.0f / HD) + EPS);
;         const size_t row = (size_t)(row0 + t);
;         const v2u gp = *(const v2u*)(Gg + row * RW + h * HD + 4 * lane);
;         const float g0 = bf2f((bf16)(gp.x & 0xffffu)), g1 = bf2f((bf16)(gp.x >> 16)), g2 = bf2f((bf16)(gp.y & 0xffffu)), g3 = bf2f((bf16)(gp.y >> 16));
;         *(GAS unsigned*)(WSP(unsigned char, WS_MIX) + row * DM + PW + h * HD + 4 * lane) = pg8::pk4_fp8(silu1(g0) * o[0] * rs, silu1(g1) * o[1] * rs, silu1(g2) * o[2] * rs, silu1(g3) * o[3] * rs);
.LBB0_1015:
	v_mul_f32_e32 v3, v17, v17
	v_mul_f32_e32 v4, v15, v15
	v_fmac_f32_e32 v3, v16, v16
	v_fmac_f32_e32 v4, v14, v14
	v_add_f32_e32 v3, v3, v4
	ds_bpermute_b32 v4, v143, v3
	s_mov_b32 s0, 0xf800000
	v_readlane_b32 s3, v252, 0
	v_lshlrev_b32_e32 v2, 2, v104
	v_readlane_b32 s36, v253, 42
	s_waitcnt lgkmcnt(0)
	v_add_f32_e32 v3, v3, v4
	ds_bpermute_b32 v4, v144, v3
	v_readlane_b32 s50, v253, 56
	v_readlane_b32 s51, v253, 57
	v_readlane_b32 s37, v253, 43
	v_readlane_b32 s38, v253, 44
	s_waitcnt lgkmcnt(0)
	v_add_f32_e32 v3, v3, v4
	ds_bpermute_b32 v4, v145, v3
	v_readlane_b32 s39, v253, 45
	v_readlane_b32 s40, v253, 46
	v_readlane_b32 s41, v253, 47
	v_readlane_b32 s42, v253, 48
	s_waitcnt lgkmcnt(0)
	v_add_f32_e32 v3, v3, v4
	ds_bpermute_b32 v4, v146, v3
	v_readlane_b32 s43, v253, 49
	v_readlane_b32 s44, v253, 50
	v_readlane_b32 s45, v253, 51
	v_readlane_b32 s46, v253, 52
	s_waitcnt lgkmcnt(0)
	v_add_f32_e32 v3, v3, v4
	ds_bpermute_b32 v4, v147, v3
	v_readlane_b32 s47, v253, 53
	v_readlane_b32 s48, v253, 54
	v_readlane_b32 s49, v253, 55
	s_waitcnt lgkmcnt(0)
	v_add_f32_e32 v3, v3, v4
	ds_bpermute_b32 v4, v148, v3
	s_waitcnt lgkmcnt(0)
	v_add_f32_e32 v3, v3, v4
	v_fmamk_f32 v3, v3, 0x3b800000, v137
	v_cmp_gt_f32_e32 vcc, s0, v3
	v_mul_f32_e32 v4, 0x4f800000, v3
	s_nop 0
	v_cndmask_b32_e32 v3, v3, v4, vcc
	v_sqrt_f32_e32 v4, v3
	s_nop 0
	v_add_u32_e32 v5, -1, v4
	v_fma_f32 v6, -v5, v4, v3
	v_cmp_ge_f32_e64 s[0:1], 0, v6
	v_add_u32_e32 v6, 1, v4
	s_nop 0
	v_cndmask_b32_e64 v5, v4, v5, s[0:1]
	v_fma_f32 v4, -v6, v4, v3
	v_cmp_lt_f32_e64 s[0:1], 0, v4
	s_nop 1
	v_cndmask_b32_e64 v4, v5, v6, s[0:1]
	v_mul_f32_e32 v5, 0x37800000, v4
	v_cndmask_b32_e32 v4, v4, v5, vcc
	v_cmp_class_f32_e32 vcc, v3, v138
	s_nop 1
	v_cndmask_b32_e32 v3, v4, v3, vcc
	v_div_scale_f32 v4, s[0:1], v3, v3, 1.0
	v_rcp_f32_e32 v5, v4
	v_readlane_b32 s0, v253, 61
	s_or_b32 s0, s27, s0
	s_ashr_i32 s1, s0, 31
	v_fma_f32 v6, -v4, v5, 1.0
	v_fmac_f32_e32 v5, v6, v5
	v_div_scale_f32 v6, vcc, 1.0, v3, 1.0
	v_mul_f32_e32 v7, v6, v5
	v_fma_f32 v8, -v4, v7, v6
	s_lshl_b64 s[0:1], s[0:1], 11
	v_fmac_f32_e32 v7, v8, v5
	s_add_u32 s22, s3, s0
	v_readlane_b32 s3, v252, 1
	v_fma_f32 v4, -v4, v7, v6
	s_addc_u32 s23, s3, s1
	s_lshl_b32 s3, s26, 8
	s_lshl_b32 s24, s26, 9
	v_div_fmas_f32 v4, v4, v5, v7
	s_add_u32 s22, s22, s24
	v_div_fixup_f32 v6, v4, v3, 1.0
	s_addc_u32 s23, s23, 0
	v_ashrrev_i32_e32 v3, 31, v2
	v_lshl_add_u64 v[4:5], v[2:3], 1, s[22:23]
	global_load_dwordx2 v[4:5], v[4:5], off nt
	s_mov_b32 s22, 0xc3e00000
	s_add_u32 s0, s50, s0
	s_addc_u32 s1, s51, s1
	s_add_u32 s0, s0, s3
	s_addc_u32 s1, s1, 0
	v_readlane_b32 s36, v253, 26
	v_lshl_add_u64 v[2:3], s[0:1], 0, v[2:3]
	v_readlane_b32 s38, v253, 28
	v_readlane_b32 s39, v253, 29
	v_readlane_b32 s40, v253, 30
	v_readlane_b32 s41, v253, 31
	v_readlane_b32 s42, v253, 32
	v_readlane_b32 s43, v253, 33
	v_readlane_b32 s44, v253, 34
	v_readlane_b32 s45, v253, 35
	v_add_co_u32_e32 v2, vcc, 0x19600000, v2
	v_readlane_b32 s37, v253, 27
	v_readlane_b32 s48, v253, 38
	v_readlane_b32 s49, v253, 39
	v_readlane_b32 s50, v253, 40
	v_readlane_b32 s51, v253, 41
	v_readlane_b32 s38, v252, 24
	v_readlane_b32 s40, v252, 26
	v_readlane_b32 s42, v252, 28
	v_readlane_b32 s44, v252, 30
	v_addc_co_u32_e32 v3, vcc, 0, v3, vcc
	v_readlane_b32 s46, v253, 36
	v_readlane_b32 s47, v253, 37
	v_readlane_b32 s36, v252, 22
	v_readlane_b32 s37, v252, 23
	v_readlane_b32 s39, v252, 25
	v_readlane_b32 s41, v252, 27
	v_readlane_b32 s43, v252, 29
	v_readlane_b32 s45, v252, 31
	v_readlane_b32 s48, v252, 32
	v_readlane_b32 s49, v252, 33
	v_readlane_b32 s50, v252, 34
	v_readlane_b32 s51, v252, 35
	s_waitcnt vmcnt(0)
	v_lshlrev_b32_e32 v7, 16, v4
	v_mul_f32_e32 v9, 0xbfb8aa3b, v7
	v_exp_f32_e32 v9, v9
	v_and_b32_e32 v4, 0xffff0000, v4
	v_lshlrev_b32_e32 v8, 16, v5
	v_and_b32_e32 v5, 0xffff0000, v5
	v_add_f32_e32 v9, 1.0, v9
	v_rcp_f32_e32 v9, v9
	s_nop 0
	v_mul_f32_e32 v7, v9, v7
	v_mul_f32_e32 v9, 0xbfb8aa3b, v4
	v_exp_f32_e32 v9, v9
	v_mul_f32_e32 v7, v16, v7
	v_mul_f32_e32 v7, v6, v7
	v_add_f32_e32 v9, 1.0, v9
	v_rcp_f32_e32 v9, v9
	s_nop 0
	v_mul_f32_e32 v4, v9, v4
	v_mul_f32_e32 v9, 0xbfb8aa3b, v8
	v_exp_f32_e32 v9, v9
	v_mul_f32_e32 v4, v17, v4
	v_mul_f32_e32 v4, v6, v4
	v_med3_f32 v4, v4, s22, v141
	v_add_f32_e32 v9, 1.0, v9
	v_rcp_f32_e32 v9, v9
	s_nop 0
	v_mul_f32_e32 v8, v9, v8
	v_mul_f32_e32 v9, 0xbfb8aa3b, v5
	v_exp_f32_e32 v9, v9
	v_mul_f32_e32 v8, v14, v8
	v_mul_f32_e32 v8, v6, v8
	v_add_f32_e32 v9, 1.0, v9
	v_rcp_f32_e32 v9, v9
	s_nop 0
	v_mul_f32_e32 v5, v9, v5
	v_mul_f32_e32 v5, v15, v5
	v_mul_f32_e32 v5, v6, v5
	v_med3_f32 v6, v7, s22, v141
	v_mov_b32_e32 v7, 0
	v_cvt_pk_fp8_f32 v7, v6, v4
	v_med3_f32 v4, v8, s22, v141
	v_med3_f32 v5, v5, s22, v141
	v_cvt_pk_fp8_f32 v7, v4, v5 op_sel:[0,0,1]
	global_store_dword v[2:3], v7, off offset:1024

; __device__ __forceinline__ void scan_states(Frame& F) {
;     ...
;     for (int i = i0; i < i1; i += istep) {
;         const int bh = i >> 13, e8 = i & 8191, h = bh & 3;
;         const bf16* up = WSP(bf16, WS_UT) + ((size_t)bh * NCH * 8192 + e8) * 8;
;         v4u uv[16];
; #pragma unroll
;         for (int c = 0; c < 16; ++c) uv[c] = *(const v4u*)(up + (size_t)c * 65536);
;         const float g128 = __builtin_amdgcn_exp2f(128.0f * log2_gamma(h));
.LBB0_1051:
	v_ashrrev_i32_e32 v68, 13, v1
	v_ashrrev_i32_e32 v69, 31, v68
	v_and_b32_e32 v73, 0x1fff, v1
	v_lshlrev_b64 v[2:3], 21, v[68:69]
	v_lshl_add_u64 v[2:3], s[2:3], 0, v[2:3]
	v_lshlrev_b32_e32 v66, 4, v73
	v_lshl_add_u64 v[2:3], v[2:3], 0, v[66:67]
	v_add_co_u32_e32 v4, vcc, 0x20000, v2
	v_and_b32_e32 v74, 3, v68
	s_nop 0
	v_addc_co_u32_e32 v5, vcc, 0, v3, vcc
	global_load_dwordx4 v[62:65], v[2:3], off nt
	global_load_dwordx4 v[58:61], v[4:5], off nt
	v_add_co_u32_e32 v4, vcc, 0x40000, v2
	v_mov_b32_e32 v70, 0xc0bb9ca6
	s_nop 0
	v_addc_co_u32_e32 v5, vcc, 0, v3, vcc
	v_add_co_u32_e32 v6, vcc, 0x60000, v2
	s_nop 1
	v_addc_co_u32_e32 v7, vcc, 0, v3, vcc
	global_load_dwordx4 v[54:57], v[4:5], off nt
	global_load_dwordx4 v[50:53], v[6:7], off nt
	v_add_co_u32_e32 v4, vcc, 0x80000, v2
	s_nop 1
	v_addc_co_u32_e32 v5, vcc, 0, v3, vcc
	v_add_co_u32_e32 v6, vcc, 0xa0000, v2
	s_nop 1
	v_addc_co_u32_e32 v7, vcc, 0, v3, vcc
	global_load_dwordx4 v[46:49], v[4:5], off nt
	global_load_dwordx4 v[42:45], v[6:7], off nt
	v_add_co_u32_e32 v4, vcc, 0xc0000, v2
	s_nop 1
	v_addc_co_u32_e32 v5, vcc, 0, v3, vcc
	v_add_co_u32_e32 v6, vcc, 0xe0000, v2
	s_nop 1
	v_addc_co_u32_e32 v7, vcc, 0, v3, vcc
	global_load_dwordx4 v[38:41], v[4:5], off nt
	global_load_dwordx4 v[34:37], v[6:7], off nt
	v_add_co_u32_e32 v4, vcc, 0x100000, v2
	s_nop 1
	v_addc_co_u32_e32 v5, vcc, 0, v3, vcc
	v_add_co_u32_e32 v6, vcc, 0x120000, v2
	s_nop 1
	v_addc_co_u32_e32 v7, vcc, 0, v3, vcc
	global_load_dwordx4 v[30:33], v[4:5], off nt
	global_load_dwordx4 v[26:29], v[6:7], off nt
	v_add_co_u32_e32 v4, vcc, 0x140000, v2
	s_nop 1
	v_addc_co_u32_e32 v5, vcc, 0, v3, vcc
	v_add_co_u32_e32 v6, vcc, 0x160000, v2
	s_nop 1
	v_addc_co_u32_e32 v7, vcc, 0, v3, vcc
	global_load_dwordx4 v[22:25], v[4:5], off nt
	global_load_dwordx4 v[18:21], v[6:7], off nt
	v_add_co_u32_e32 v4, vcc, 0x180000, v2
	s_nop 1
	v_addc_co_u32_e32 v5, vcc, 0, v3, vcc
	v_add_co_u32_e32 v6, vcc, 0x1a0000, v2
	s_nop 1
	v_addc_co_u32_e32 v7, vcc, 0, v3, vcc
	global_load_dwordx4 v[14:17], v[4:5], off nt
	global_load_dwordx4 v[10:13], v[6:7], off nt
	v_add_co_u32_e32 v4, vcc, 0x1c0000, v2
	s_nop 1
	v_addc_co_u32_e32 v5, vcc, 0, v3, vcc
	v_add_co_u32_e32 v2, vcc, 0x1e0000, v2
	s_nop 1
	v_addc_co_u32_e32 v3, vcc, 0, v3, vcc
	global_load_dwordx4 v[6:9], v[4:5], off nt
	s_nop 0
	global_load_dwordx4 v[2:5], v[2:3], off nt
	v_cmp_lt_i32_e32 vcc, 0, v74
	s_and_saveexec_b64 s[10:11], vcc
	s_cbranch_execz .LBB0_1050
	v_cmp_ne_u32_e32 vcc, 1, v74
	s_and_saveexec_b64 s[12:13], vcc
	s_xor_b64 s[12:13], exec, s[12:13]
	v_cmp_eq_u32_e32 vcc, 2, v74
	s_nop 1
	v_cndmask_b32_e32 v70, v71, v72, vcc
	s_andn2_saveexec_b64 s[12:13], s[12:13]
	s_cbranch_execz .LBB0_1049
	v_mov_b32_e32 v70, 0xc03a1f74
	s_branch .LBB0_1049
